# P7 K-loop: inverted s_setprio roles (memory-phase wave prio 1, MFMA-phase wave prio 0, mid-phase flips removed)
# speedup vs baseline: 1.0042x; 1.0042x over previous
; #define G8_STAGE(bufoff, gbase, NM) do { _Pragma("unroll") for (int _i = 0; _i < 2; ++_i) { \
;     const char* _b = (const char*)(gbase) + (_i ? p2##NM : (size_t)0); asm volatile("" : "+s"(_b));     \
;     __builtin_amdgcn_global_load_lds((const unsigned*)(_b + voff##NM), (LAS unsigned*)(lds + (bufoff) + ldsw + _i * 8192), 16, 0, 0); } } while (0)
; #define G8_WAIT_V(n) asm volatile("s_waitcnt vmcnt(" #n ")" ::: "memory")
; #define G8_WAIT_L(n) asm volatile("s_waitcnt lgkmcnt(" #n ")" ::: "memory")
; #define G8_BAR __builtin_amdgcn_s_barrier()
; #define G8_SCHED __builtin_amdgcn_sched_barrier(0)
;     ...
;     for (int t = 0; t < nt; t += 2) {
;       const bool last = (t == nt - 2);
;       const char* a1 = cA + (size_t)(t + 1) * kstep + hstepA;
;       const char* a2 = last ? nA : cA + (size_t)(t + 2) * kstep; const char* b2 = last ? nB : cB + (size_t)(t + 2) * kstep;
;       const char* a3 = a2 + kstep; const char* b3 = b2 + kstep;
;       asm volatile("" : "+s"(a1), "+s"(a2), "+s"(b2), "+s"(a3), "+s"(b3));
;       G8_LDB(B0, 0, 0); G8_LDB(B1, 0, 1); G8_SCHED; G8_LDA(At, 0, 0); G8_STAGE(G8_SA(1, 1), a1, A);
;       const bool d0a = (BD == 0) || (BD == 1 && t < (nt >> 1)) || (BD == 2 && !(cur.pn & 1));
;       const bool d1a = (BD == 0) || (BD == 1 && t >= (nt >> 1)) || (BD == 2 && !(cur.pn & 1));
;       const bool d0b = (BD == 0) || (BD == 1 && t < (nt >> 1)) || (BD == 2 && (cur.pn & 1));
;       const bool d1b = (BD == 0) || (BD == 1 && t >= (nt >> 1)) || (BD == 2 && (cur.pn & 1));
;       G8_WAIT_V(8); G8_WAIT_L(0); G8_BAR; if (d0a) G8_MMA(0, 0, At, B0); if (d1a) G8_MMA(0, 1, At, B1); G8_BAR; G8_SCHED;
;       G8_LDA(At, 0, 1); G8_STAGE(G8_SB(0, 0), b2, B); G8_STAGE(G8_SB(0, 1), b2 + hstepB, B); G8_STAGE(G8_SA(0, 0), a2, A);
;       G8_WAIT_V(8); G8_WAIT_L(0); G8_BAR; if (d0a) G8_MMA(1, 0, At, B0); if (d1a) G8_MMA(1, 1, At, B1); G8_BAR; G8_SCHED;
.LBB0_1125:
	s_cmp_eq_u32 s54, 28
	s_cselect_b32 s30, s22, s50
	s_cselect_b32 s31, s23, s51
	s_cselect_b32 s35, s25, s53
	s_cselect_b32 s34, s24, s52
	s_add_u32 s26, s30, 0x80
	s_addc_u32 s27, s31, 0
	s_add_u32 s28, s34, 0x80
	s_addc_u32 s29, s35, 0
	s_mov_b64 s[56:57], s[4:5]
	ds_read_b128 v[134:137], v141
	ds_read_b128 v[146:149], v141 offset:1024
	ds_read_b128 v[150:153], v141 offset:2048
	ds_read_b128 v[154:157], v141 offset:3072
	ds_read_b128 v[158:161], v142
	ds_read_b128 v[162:165], v142 offset:1024
	ds_read_b128 v[166:169], v142 offset:2048
	ds_read_b128 v[170:173], v142 offset:3072
	s_add_i32 m0, s1, 0xc000
	s_mov_b64 s[58:59], s[56:57]
	s_add_u32 s56, s56, 0x42000
	ds_read_b128 v[174:177], v143
	ds_read_b128 v[178:181], v143 offset:1024
	ds_read_b128 v[182:185], v143 offset:2048
	ds_read_b128 v[186:189], v143 offset:3072
	ds_read_b128 v[190:193], v143 offset:4096
	ds_read_b128 v[194:197], v143 offset:5120
	ds_read_b128 v[202:205], v143 offset:6144
	ds_read_b128 v[206:209], v143 offset:7168
	s_addc_u32 s57, s57, 0
	v_lshl_add_u64 v[138:139], s[58:59], 0, v[128:129]
	global_load_lds_dwordx4 v[138:139], off
	s_add_i32 m0, s1, 0xe000
	v_lshl_add_u64 v[138:139], s[56:57], 0, v[128:129]
	global_load_lds_dwordx4 v[138:139], off
	s_waitcnt vmcnt(8)
	s_waitcnt lgkmcnt(0)
	s_barrier
	s_setprio 0
	s_waitcnt lgkmcnt(0)
	v_mfma_f32_16x16x32_bf16 v[124:127], v[134:137], v[174:177], v[124:127]
	v_mfma_f32_16x16x32_bf16 v[120:123], v[150:153], v[174:177], v[120:123]
	v_mfma_f32_16x16x32_bf16 v[108:111], v[134:137], v[182:185], v[108:111]
	v_mfma_f32_16x16x32_bf16 v[104:107], v[150:153], v[182:185], v[104:107]
	v_mfma_f32_16x16x32_bf16 v[92:95], v[134:137], v[190:193], v[92:95]
	v_mfma_f32_16x16x32_bf16 v[88:91], v[150:153], v[190:193], v[88:91]
	v_mfma_f32_16x16x32_bf16 v[76:79], v[134:137], v[202:205], v[76:79]
	v_mfma_f32_16x16x32_bf16 v[72:75], v[150:153], v[202:205], v[72:75]
	v_mfma_f32_16x16x32_bf16 v[124:127], v[146:149], v[178:181], v[124:127]
	v_mfma_f32_16x16x32_bf16 v[120:123], v[154:157], v[178:181], v[120:123]
	v_mfma_f32_16x16x32_bf16 v[108:111], v[146:149], v[186:189], v[108:111]
	v_mfma_f32_16x16x32_bf16 v[104:107], v[154:157], v[186:189], v[104:107]
	v_mfma_f32_16x16x32_bf16 v[92:95], v[146:149], v[194:197], v[92:95]
	v_mfma_f32_16x16x32_bf16 v[88:91], v[154:157], v[194:197], v[88:91]
	v_mfma_f32_16x16x32_bf16 v[76:79], v[146:149], v[206:209], v[76:79]
	v_mfma_f32_16x16x32_bf16 v[72:75], v[154:157], v[206:209], v[72:75]
	v_mfma_f32_16x16x32_bf16 v[116:119], v[158:161], v[174:177], v[116:119]
	v_mfma_f32_16x16x32_bf16 v[112:115], v[166:169], v[174:177], v[112:115]
	v_mfma_f32_16x16x32_bf16 v[100:103], v[158:161], v[182:185], v[100:103]
	v_mfma_f32_16x16x32_bf16 v[96:99], v[166:169], v[182:185], v[96:99]
	v_mfma_f32_16x16x32_bf16 v[84:87], v[158:161], v[190:193], v[84:87]
	v_mfma_f32_16x16x32_bf16 v[80:83], v[166:169], v[190:193], v[80:83]
	v_mfma_f32_16x16x32_bf16 v[68:71], v[158:161], v[202:205], v[68:71]
	v_mfma_f32_16x16x32_bf16 v[64:67], v[166:169], v[202:205], v[64:67]
	v_mfma_f32_16x16x32_bf16 v[116:119], v[162:165], v[178:181], v[116:119]
	v_mfma_f32_16x16x32_bf16 v[112:115], v[170:173], v[178:181], v[112:115]
	v_mfma_f32_16x16x32_bf16 v[100:103], v[162:165], v[186:189], v[100:103]
	v_mfma_f32_16x16x32_bf16 v[96:99], v[170:173], v[186:189], v[96:99]
	v_mfma_f32_16x16x32_bf16 v[84:87], v[162:165], v[194:197], v[84:87]
	v_mfma_f32_16x16x32_bf16 v[80:83], v[170:173], v[194:197], v[80:83]
	v_mfma_f32_16x16x32_bf16 v[68:71], v[162:165], v[206:209], v[68:71]
	v_mfma_f32_16x16x32_bf16 v[64:67], v[170:173], v[206:209], v[64:67]
	s_setprio 1
	s_barrier
	s_mov_b64 s[56:57], s[34:35]
	ds_read_b128 v[174:177], v143 offset:16384
	ds_read_b128 v[178:181], v143 offset:17408
	ds_read_b128 v[182:185], v143 offset:18432
	ds_read_b128 v[186:189], v143 offset:19456
	ds_read_b128 v[190:193], v143 offset:20480
	ds_read_b128 v[194:197], v143 offset:21504
	ds_read_b128 v[202:205], v143 offset:22528
	ds_read_b128 v[206:209], v143 offset:23552
	s_add_i32 s55, s39, s0
	v_lshl_add_u64 v[138:139], s[56:57], 0, v[130:131]
	s_add_u32 s56, s34, 0x42000
	s_mov_b32 m0, s55
	s_addc_u32 s57, s35, 0
	global_load_lds_dwordx4 v[138:139], off
	s_add_i32 m0, s55, 0x2000
	v_lshl_add_u64 v[138:139], s[56:57], 0, v[130:131]
	s_add_u32 s56, s34, 0x84000
	s_addc_u32 s57, s35, 0
	s_add_i32 s55, s40, s0
	s_add_u32 s34, s34, 0xc6000
	global_load_lds_dwordx4 v[138:139], off
	s_mov_b32 m0, s55
	v_lshl_add_u64 v[138:139], s[56:57], 0, v[130:131]
	s_addc_u32 s35, s35, 0
	global_load_lds_dwordx4 v[138:139], off
	s_add_i32 m0, s55, 0x2000
	v_lshl_add_u64 v[138:139], s[34:35], 0, v[130:131]
	s_mov_b64 s[34:35], s[30:31]
	global_load_lds_dwordx4 v[138:139], off
	s_mov_b32 m0, s1
	v_lshl_add_u64 v[138:139], s[34:35], 0, v[128:129]
	s_add_u32 s34, s30, 0x42000
	s_addc_u32 s35, s31, 0
	global_load_lds_dwordx4 v[138:139], off
	s_mov_b32 m0, s2
	v_lshl_add_u64 v[138:139], s[34:35], 0, v[128:129]
	global_load_lds_dwordx4 v[138:139], off
	s_waitcnt vmcnt(8)
	s_waitcnt lgkmcnt(0)
	s_barrier
; #define G8_STAGE(bufoff, gbase, NM) do { _Pragma("unroll") for (int _i = 0; _i < 2; ++_i) { \
;     const char* _b = (const char*)(gbase) + (_i ? p2##NM : (size_t)0); asm volatile("" : "+s"(_b));     \
;     __builtin_amdgcn_global_load_lds((const unsigned*)(_b + voff##NM), (LAS unsigned*)(lds + (bufoff) + ldsw + _i * 8192), 16, 0, 0); } } while (0)
; #define G8_WAIT_V(n) asm volatile("s_waitcnt vmcnt(" #n ")" ::: "memory")
; #define G8_WAIT_L(n) asm volatile("s_waitcnt lgkmcnt(" #n ")" ::: "memory")
; #define G8_BAR __builtin_amdgcn_s_barrier()
; #define G8_SCHED __builtin_amdgcn_sched_barrier(0)
;     ...
;       G8_WAIT_V(8); G8_WAIT_L(0); G8_BAR; if (d0a) G8_MMA(0, 0, At, B0); if (d1a) G8_MMA(0, 1, At, B1); G8_BAR; G8_SCHED;
;       G8_LDA(At, 0, 1); G8_STAGE(G8_SB(0, 0), b2, B); G8_STAGE(G8_SB(0, 1), b2 + hstepB, B); G8_STAGE(G8_SA(0, 0), a2, A);
;       G8_WAIT_V(8); G8_WAIT_L(0); G8_BAR; if (d0a) G8_MMA(1, 0, At, B0); if (d1a) G8_MMA(1, 1, At, B1); G8_BAR; G8_SCHED;
;       G8_LDB(B0, 1, 0); G8_LDB(B1, 1, 1); G8_SCHED; G8_LDA(At, 1, 0); G8_STAGE(G8_SA(0, 1), a2 + hstepA, A);
;       G8_WAIT_V(8); G8_WAIT_L(0); G8_BAR; if (d0b) G8_MMA(0, 0, At, B0); if (d1b) G8_MMA(0, 1, At, B1); G8_BAR; G8_SCHED;
	s_setprio 0
	s_waitcnt lgkmcnt(0)
	v_mfma_f32_16x16x32_bf16 v[60:63], v[134:137], v[174:177], v[60:63]
	v_mfma_f32_16x16x32_bf16 v[56:59], v[150:153], v[174:177], v[56:59]
	v_mfma_f32_16x16x32_bf16 v[44:47], v[134:137], v[182:185], v[44:47]
	v_mfma_f32_16x16x32_bf16 v[40:43], v[150:153], v[182:185], v[40:43]
	v_mfma_f32_16x16x32_bf16 v[28:31], v[134:137], v[190:193], v[28:31]
	v_mfma_f32_16x16x32_bf16 v[24:27], v[150:153], v[190:193], v[24:27]
	v_mfma_f32_16x16x32_bf16 v[12:15], v[134:137], v[202:205], v[12:15]
	v_mfma_f32_16x16x32_bf16 v[8:11], v[150:153], v[202:205], v[8:11]
	v_mfma_f32_16x16x32_bf16 v[60:63], v[146:149], v[178:181], v[60:63]
	v_mfma_f32_16x16x32_bf16 v[56:59], v[154:157], v[178:181], v[56:59]
	v_mfma_f32_16x16x32_bf16 v[44:47], v[146:149], v[186:189], v[44:47]
	v_mfma_f32_16x16x32_bf16 v[40:43], v[154:157], v[186:189], v[40:43]
	v_mfma_f32_16x16x32_bf16 v[28:31], v[146:149], v[194:197], v[28:31]
	v_mfma_f32_16x16x32_bf16 v[24:27], v[154:157], v[194:197], v[24:27]
	v_mfma_f32_16x16x32_bf16 v[12:15], v[146:149], v[206:209], v[12:15]
	v_mfma_f32_16x16x32_bf16 v[8:11], v[154:157], v[206:209], v[8:11]
	v_mfma_f32_16x16x32_bf16 v[52:55], v[158:161], v[174:177], v[52:55]
	v_mfma_f32_16x16x32_bf16 v[48:51], v[166:169], v[174:177], v[48:51]
	v_mfma_f32_16x16x32_bf16 v[36:39], v[158:161], v[182:185], v[36:39]
	v_mfma_f32_16x16x32_bf16 v[32:35], v[166:169], v[182:185], v[32:35]
	v_mfma_f32_16x16x32_bf16 v[20:23], v[158:161], v[190:193], v[20:23]
	v_mfma_f32_16x16x32_bf16 v[16:19], v[166:169], v[190:193], v[16:19]
	v_mfma_f32_16x16x32_bf16 v[4:7], v[158:161], v[202:205], v[4:7]
	v_mfma_f32_16x16x32_bf16 v[0:3], v[166:169], v[202:205], v[0:3]
	v_mfma_f32_16x16x32_bf16 v[52:55], v[162:165], v[178:181], v[52:55]
	v_mfma_f32_16x16x32_bf16 v[48:51], v[170:173], v[178:181], v[48:51]
	v_mfma_f32_16x16x32_bf16 v[36:39], v[162:165], v[186:189], v[36:39]
	v_mfma_f32_16x16x32_bf16 v[32:35], v[170:173], v[186:189], v[32:35]
	v_mfma_f32_16x16x32_bf16 v[20:23], v[162:165], v[194:197], v[20:23]
	v_mfma_f32_16x16x32_bf16 v[16:19], v[170:173], v[194:197], v[16:19]
	v_mfma_f32_16x16x32_bf16 v[4:7], v[162:165], v[206:209], v[4:7]
	v_mfma_f32_16x16x32_bf16 v[0:3], v[170:173], v[206:209], v[0:3]
	s_setprio 1
	s_barrier
	s_add_i32 s55, 0, 0x18000
	v_add_u32_e32 v132, s55, v140
	s_add_i32 s56, 0, 0x1c000
	ds_read_b128 v[134:137], v132
	ds_read_b128 v[146:149], v132 offset:1024
	ds_read_b128 v[150:153], v132 offset:2048
	ds_read_b128 v[154:157], v132 offset:3072
	v_add_u32_e32 v132, 0x1000, v132
	ds_read_b128 v[158:161], v132
	ds_read_b128 v[162:165], v132 offset:1024
	ds_read_b128 v[166:169], v132 offset:2048
	ds_read_b128 v[170:173], v132 offset:3072
	s_add_u32 s34, s30, 0x84000
	s_addc_u32 s35, s31, 0
	s_add_u32 s30, s30, 0xc6000
	s_mov_b32 m0, s3
	ds_read_b128 v[174:177], v143 offset:32768
	ds_read_b128 v[178:181], v143 offset:33792
	ds_read_b128 v[182:185], v143 offset:34816
	ds_read_b128 v[186:189], v143 offset:35840
	ds_read_b128 v[190:193], v143 offset:36864
	ds_read_b128 v[194:197], v143 offset:37888
	ds_read_b128 v[202:205], v143 offset:38912
	ds_read_b128 v[206:209], v143 offset:39936
	s_addc_u32 s31, s31, 0
	v_lshl_add_u64 v[138:139], s[34:35], 0, v[128:129]
	global_load_lds_dwordx4 v[138:139], off
	s_mov_b32 m0, s33
	v_lshl_add_u64 v[138:139], s[30:31], 0, v[128:129]
	global_load_lds_dwordx4 v[138:139], off
	s_waitcnt vmcnt(8)
	s_waitcnt lgkmcnt(0)
	s_barrier
	s_setprio 0
	s_waitcnt lgkmcnt(0)
	v_mfma_f32_16x16x32_bf16 v[124:127], v[134:137], v[174:177], v[124:127]
	v_mfma_f32_16x16x32_bf16 v[120:123], v[150:153], v[174:177], v[120:123]
	v_mfma_f32_16x16x32_bf16 v[108:111], v[134:137], v[182:185], v[108:111]
	v_mfma_f32_16x16x32_bf16 v[104:107], v[150:153], v[182:185], v[104:107]
	v_mfma_f32_16x16x32_bf16 v[92:95], v[134:137], v[190:193], v[92:95]
	v_mfma_f32_16x16x32_bf16 v[88:91], v[150:153], v[190:193], v[88:91]
	v_mfma_f32_16x16x32_bf16 v[76:79], v[134:137], v[202:205], v[76:79]
	v_mfma_f32_16x16x32_bf16 v[72:75], v[150:153], v[202:205], v[72:75]
	v_mfma_f32_16x16x32_bf16 v[124:127], v[146:149], v[178:181], v[124:127]
	v_mfma_f32_16x16x32_bf16 v[120:123], v[154:157], v[178:181], v[120:123]
	v_mfma_f32_16x16x32_bf16 v[108:111], v[146:149], v[186:189], v[108:111]
	v_mfma_f32_16x16x32_bf16 v[104:107], v[154:157], v[186:189], v[104:107]
	v_mfma_f32_16x16x32_bf16 v[92:95], v[146:149], v[194:197], v[92:95]
	v_mfma_f32_16x16x32_bf16 v[88:91], v[154:157], v[194:197], v[88:91]
	v_mfma_f32_16x16x32_bf16 v[76:79], v[146:149], v[206:209], v[76:79]
	v_mfma_f32_16x16x32_bf16 v[72:75], v[154:157], v[206:209], v[72:75]
	v_mfma_f32_16x16x32_bf16 v[116:119], v[158:161], v[174:177], v[116:119]
	v_mfma_f32_16x16x32_bf16 v[112:115], v[166:169], v[174:177], v[112:115]
	v_mfma_f32_16x16x32_bf16 v[100:103], v[158:161], v[182:185], v[100:103]
	v_mfma_f32_16x16x32_bf16 v[96:99], v[166:169], v[182:185], v[96:99]
	v_mfma_f32_16x16x32_bf16 v[84:87], v[158:161], v[190:193], v[84:87]
	v_mfma_f32_16x16x32_bf16 v[80:83], v[166:169], v[190:193], v[80:83]
	v_mfma_f32_16x16x32_bf16 v[68:71], v[158:161], v[202:205], v[68:71]
	v_mfma_f32_16x16x32_bf16 v[64:67], v[166:169], v[202:205], v[64:67]
	v_mfma_f32_16x16x32_bf16 v[116:119], v[162:165], v[178:181], v[116:119]
	v_mfma_f32_16x16x32_bf16 v[112:115], v[170:173], v[178:181], v[112:115]
	v_mfma_f32_16x16x32_bf16 v[100:103], v[162:165], v[186:189], v[100:103]
	v_mfma_f32_16x16x32_bf16 v[96:99], v[170:173], v[186:189], v[96:99]
	v_mfma_f32_16x16x32_bf16 v[84:87], v[162:165], v[194:197], v[84:87]
	v_mfma_f32_16x16x32_bf16 v[80:83], v[170:173], v[194:197], v[80:83]
	v_mfma_f32_16x16x32_bf16 v[68:71], v[162:165], v[206:209], v[68:71]
	v_mfma_f32_16x16x32_bf16 v[64:67], v[170:173], v[206:209], v[64:67]
	s_setprio 1
	s_barrier
; #define G8_STAGE(bufoff, gbase, NM) do { _Pragma("unroll") for (int _i = 0; _i < 2; ++_i) { \
;     const char* _b = (const char*)(gbase) + (_i ? p2##NM : (size_t)0); asm volatile("" : "+s"(_b));     \
;     __builtin_amdgcn_global_load_lds((const unsigned*)(_b + voff##NM), (LAS unsigned*)(lds + (bufoff) + ldsw + _i * 8192), 16, 0, 0); } } while (0)
; #define G8_WAIT_V(n) asm volatile("s_waitcnt vmcnt(" #n ")" ::: "memory")
; #define G8_WAIT_L(n) asm volatile("s_waitcnt lgkmcnt(" #n ")" ::: "memory")
; #define G8_BAR __builtin_amdgcn_s_barrier()
; #define G8_SCHED __builtin_amdgcn_sched_barrier(0)
;     ...
;       G8_LDA(At, 1, 1); G8_STAGE(G8_SB(1, 0), b3, B); G8_STAGE(G8_SB(1, 1), b3 + hstepB, B); G8_STAGE(G8_SA(1, 0), a3, A);
;       G8_WAIT_V(8); G8_WAIT_L(0); G8_BAR; if (d0b) G8_MMA(1, 0, At, B0); if (d1b) G8_MMA(1, 1, At, B1); G8_BAR; G8_SCHED;
;     }
;     if (wr == 0) G8_BAR;
	s_mov_b64 s[30:31], s[28:29]
	ds_read_b128 v[174:177], v143 offset:49152
	ds_read_b128 v[178:181], v143 offset:50176
	ds_read_b128 v[182:185], v143 offset:51200
	ds_read_b128 v[186:189], v143 offset:52224
	ds_read_b128 v[190:193], v143 offset:53248
	ds_read_b128 v[194:197], v143 offset:54272
	ds_read_b128 v[202:205], v143 offset:55296
	ds_read_b128 v[206:209], v143 offset:56320
	s_add_i32 s34, s55, s0
	v_lshl_add_u64 v[138:139], s[30:31], 0, v[130:131]
	s_add_u32 s30, s28, 0x42000
	s_mov_b32 m0, s34
	s_addc_u32 s31, s29, 0
	global_load_lds_dwordx4 v[138:139], off
	s_add_i32 m0, s34, 0x2000
	v_lshl_add_u64 v[138:139], s[30:31], 0, v[130:131]
	s_add_u32 s30, s28, 0x84000
	s_addc_u32 s31, s29, 0
	global_load_lds_dwordx4 v[138:139], off
	s_nop 0
	v_lshl_add_u64 v[138:139], s[30:31], 0, v[130:131]
	s_add_i32 s30, s56, s0
	s_add_u32 s28, s28, 0xc6000
	s_mov_b32 m0, s30
	s_addc_u32 s29, s29, 0
	global_load_lds_dwordx4 v[138:139], off
	s_add_i32 m0, s30, 0x2000
	v_lshl_add_u64 v[138:139], s[28:29], 0, v[130:131]
	s_mov_b64 s[28:29], s[26:27]
	s_add_u32 s26, s26, 0x42000
	global_load_lds_dwordx4 v[138:139], off
	s_mov_b32 m0, s37
	v_lshl_add_u64 v[138:139], s[28:29], 0, v[128:129]
	s_addc_u32 s27, s27, 0
	global_load_lds_dwordx4 v[138:139], off
	s_mov_b32 m0, s38
	v_lshl_add_u64 v[138:139], s[26:27], 0, v[128:129]
	global_load_lds_dwordx4 v[138:139], off
	s_waitcnt vmcnt(8)
	s_waitcnt lgkmcnt(0)
	s_barrier
	s_setprio 0
	s_waitcnt lgkmcnt(0)
	v_mfma_f32_16x16x32_bf16 v[60:63], v[134:137], v[174:177], v[60:63]
	v_mfma_f32_16x16x32_bf16 v[56:59], v[150:153], v[174:177], v[56:59]
	v_mfma_f32_16x16x32_bf16 v[44:47], v[134:137], v[182:185], v[44:47]
	v_mfma_f32_16x16x32_bf16 v[40:43], v[150:153], v[182:185], v[40:43]
	v_mfma_f32_16x16x32_bf16 v[28:31], v[134:137], v[190:193], v[28:31]
	v_mfma_f32_16x16x32_bf16 v[24:27], v[150:153], v[190:193], v[24:27]
	v_mfma_f32_16x16x32_bf16 v[12:15], v[134:137], v[202:205], v[12:15]
	v_mfma_f32_16x16x32_bf16 v[8:11], v[150:153], v[202:205], v[8:11]
	v_mfma_f32_16x16x32_bf16 v[60:63], v[146:149], v[178:181], v[60:63]
	v_mfma_f32_16x16x32_bf16 v[56:59], v[154:157], v[178:181], v[56:59]
	v_mfma_f32_16x16x32_bf16 v[44:47], v[146:149], v[186:189], v[44:47]
	v_mfma_f32_16x16x32_bf16 v[40:43], v[154:157], v[186:189], v[40:43]
	v_mfma_f32_16x16x32_bf16 v[28:31], v[146:149], v[194:197], v[28:31]
	v_mfma_f32_16x16x32_bf16 v[24:27], v[154:157], v[194:197], v[24:27]
	v_mfma_f32_16x16x32_bf16 v[12:15], v[146:149], v[206:209], v[12:15]
	v_mfma_f32_16x16x32_bf16 v[8:11], v[154:157], v[206:209], v[8:11]
	v_mfma_f32_16x16x32_bf16 v[52:55], v[158:161], v[174:177], v[52:55]
	v_mfma_f32_16x16x32_bf16 v[48:51], v[166:169], v[174:177], v[48:51]
	v_mfma_f32_16x16x32_bf16 v[36:39], v[158:161], v[182:185], v[36:39]
	v_mfma_f32_16x16x32_bf16 v[32:35], v[166:169], v[182:185], v[32:35]
	v_mfma_f32_16x16x32_bf16 v[20:23], v[158:161], v[190:193], v[20:23]
	v_mfma_f32_16x16x32_bf16 v[16:19], v[166:169], v[190:193], v[16:19]
	v_mfma_f32_16x16x32_bf16 v[4:7], v[158:161], v[202:205], v[4:7]
	v_mfma_f32_16x16x32_bf16 v[0:3], v[166:169], v[202:205], v[0:3]
	v_mfma_f32_16x16x32_bf16 v[52:55], v[162:165], v[178:181], v[52:55]
	v_mfma_f32_16x16x32_bf16 v[48:51], v[170:173], v[178:181], v[48:51]
	v_mfma_f32_16x16x32_bf16 v[36:39], v[162:165], v[186:189], v[36:39]
	v_mfma_f32_16x16x32_bf16 v[32:35], v[170:173], v[186:189], v[32:35]
	v_mfma_f32_16x16x32_bf16 v[20:23], v[162:165], v[194:197], v[20:23]
	v_mfma_f32_16x16x32_bf16 v[16:19], v[170:173], v[194:197], v[16:19]
	v_mfma_f32_16x16x32_bf16 v[4:7], v[162:165], v[206:209], v[4:7]
	v_mfma_f32_16x16x32_bf16 v[0:3], v[170:173], v[206:209], v[0:3]
	s_setprio 1
	s_barrier
	s_add_i32 s54, s54, 2
	s_add_u32 s50, s50, 0x100
	s_addc_u32 s51, s51, 0
	s_add_u32 s52, s52, 0x100
	s_addc_u32 s53, s53, 0
	s_add_u32 s4, s4, 0x100
	s_addc_u32 s5, s5, 0
	s_cmp_gt_u32 s54, 29
	s_cbranch_scc0 .LBB0_1125
	s_and_b64 vcc, exec, s[12:13]
	s_cbranch_vccz .LBB0_1128
	s_barrier
